# hand-scheduled QKV epilogue body: rs reads, lane sums of squares and both bpermute hops batched over the 8 rows (was one row at a time); same arithmetic
# baseline (speedup 1.0000x reference)
;     __device__ __forceinline__ void operator()(AccRef acc, const pg8::Unit& u, int wr, int wc, int fr, int fq) const {
;     ...
;         bf16* dst = (bf16*)(big + off) + lg * 64 + 8 * fq;
;         f32x4 gv[2][2];
; #pragma unroll
;         for (int bj = 0; bj < 2; ++bj)
; #pragma unroll
;             for (int n = 0; n < 2; ++n) {
;                 f32x4 g4 = {1.f, 1.f, 1.f, 1.f};
;                 if (gain) g4 = *(const f32x4*)(gain + 32 * bj + 8 * fq + 4 * n);
;                 gv[bj][n] = g4 * sc;
;             }
; #pragma unroll
;         for (int ai = 0; ai < 2; ++ai)
; #pragma unroll
;             for (int m = 0; m < 4; ++m) {
;                 const int row = row0 + ai * 128 + m * 16;
;                 const float rsr = rst[row & 255];
;                 f32x4 xv[2][2];
; #pragma unroll
;                 for (int bj = 0; bj < 2; ++bj)
; #pragma unroll
;                     for (int n = 0; n < 2; ++n) xv[bj][n] = acc[ai][bj][m][n] * rsr;
.LBB0_228:
	v_lshlrev_b32_e32 v20, 5, v244
	s_cmp_eq_u64 s[22:23], 0
	s_cbranch_scc1 .Lqkv_head
	global_load_dwordx4 v[2:5], v20, s[22:23]
	global_load_dwordx4 v[6:9], v20, s[22:23] offset:16
	global_load_dwordx4 v[10:13], v20, s[22:23] offset:128
	global_load_dwordx4 v[14:17], v20, s[22:23] offset:144
.Lqkv_head:
	v_lshlrev_b32_e32 v21, 2, v19
	v_add_u32_e32 v21, 0x20100, v21
	ds_read_b32 v48, v21 offset:0
	ds_read_b32 v50, v21 offset:64
	ds_read_b32 v52, v21 offset:128
	ds_read_b32 v54, v21 offset:192
	ds_read_b32 v56, v21 offset:512
	ds_read_b32 v58, v21 offset:576
	ds_read_b32 v60, v21 offset:640
	ds_read_b32 v62, v21 offset:704
	v_mul_lo_u32 v22, v18, s10
	v_lshlrev_b32_e32 v23, 4, v244
	v_lshl_add_u32 v22, v22, 1, v23
	v_readlane_b32 s20, v255, 23
	v_readlane_b32 s21, v255, 24
	s_add_u32 s12, s12, s20
	s_addc_u32 s13, s13, s21
	s_lshl_b32 s20, s30, 7
	s_add_u32 s12, s12, s20
	s_addc_u32 s13, s13, 0
	s_lshl_b32 s20, s10, 5
	s_mul_i32 s21, s20, 5
	s_mov_b32 s3, 0x800000
	v_and_b32_e32 v41, 64, v236
	v_xor_b32_e32 v40, 16, v236
	v_add_u32_e32 v41, 64, v41
	v_xor_b32_e32 v42, 32, v236
	v_cmp_lt_i32_e32 vcc, v40, v41
	v_cmp_lt_i32_e64 s[6:7], v42, v41
	s_nop 1
	v_cndmask_b32_e32 v40, v236, v40, vcc
	v_cndmask_b32_e64 v42, v236, v42, s[6:7]
	v_lshlrev_b32_e32 v40, 2, v40
	v_lshlrev_b32_e32 v42, 2, v42
	s_waitcnt lgkmcnt(7)
	v_pk_mul_f32 v[190:191], v[190:191], v[48:49] op_sel_hi:[1,0]
	v_pk_mul_f32 v[192:193], v[192:193], v[48:49] op_sel_hi:[1,0]
	v_pk_mul_f32 v[186:187], v[186:187], v[48:49] op_sel_hi:[1,0]
	v_pk_mul_f32 v[188:189], v[188:189], v[48:49] op_sel_hi:[1,0]
	v_pk_mul_f32 v[182:183], v[182:183], v[48:49] op_sel_hi:[1,0]
	v_pk_mul_f32 v[184:185], v[184:185], v[48:49] op_sel_hi:[1,0]
	v_pk_mul_f32 v[178:179], v[178:179], v[48:49] op_sel_hi:[1,0]
	v_pk_mul_f32 v[180:181], v[180:181], v[48:49] op_sel_hi:[1,0]
	s_waitcnt lgkmcnt(6)
	v_pk_mul_f32 v[174:175], v[174:175], v[50:51] op_sel_hi:[1,0]
	v_pk_mul_f32 v[176:177], v[176:177], v[50:51] op_sel_hi:[1,0]
	v_pk_mul_f32 v[170:171], v[170:171], v[50:51] op_sel_hi:[1,0]
	v_pk_mul_f32 v[172:173], v[172:173], v[50:51] op_sel_hi:[1,0]
	v_pk_mul_f32 v[166:167], v[166:167], v[50:51] op_sel_hi:[1,0]
	v_pk_mul_f32 v[168:169], v[168:169], v[50:51] op_sel_hi:[1,0]
	v_pk_mul_f32 v[162:163], v[162:163], v[50:51] op_sel_hi:[1,0]
	v_pk_mul_f32 v[164:165], v[164:165], v[50:51] op_sel_hi:[1,0]
	s_waitcnt lgkmcnt(5)
	v_pk_mul_f32 v[158:159], v[158:159], v[52:53] op_sel_hi:[1,0]
	v_pk_mul_f32 v[160:161], v[160:161], v[52:53] op_sel_hi:[1,0]
	v_pk_mul_f32 v[154:155], v[154:155], v[52:53] op_sel_hi:[1,0]
	v_pk_mul_f32 v[156:157], v[156:157], v[52:53] op_sel_hi:[1,0]
	v_pk_mul_f32 v[150:151], v[150:151], v[52:53] op_sel_hi:[1,0]
	v_pk_mul_f32 v[152:153], v[152:153], v[52:53] op_sel_hi:[1,0]
	v_pk_mul_f32 v[146:147], v[146:147], v[52:53] op_sel_hi:[1,0]
	v_pk_mul_f32 v[148:149], v[148:149], v[52:53] op_sel_hi:[1,0]
	s_waitcnt lgkmcnt(4)
	v_pk_mul_f32 v[142:143], v[142:143], v[54:55] op_sel_hi:[1,0]
	v_pk_mul_f32 v[144:145], v[144:145], v[54:55] op_sel_hi:[1,0]
	v_pk_mul_f32 v[138:139], v[138:139], v[54:55] op_sel_hi:[1,0]
	v_pk_mul_f32 v[140:141], v[140:141], v[54:55] op_sel_hi:[1,0]
	v_pk_mul_f32 v[134:135], v[134:135], v[54:55] op_sel_hi:[1,0]
	v_pk_mul_f32 v[136:137], v[136:137], v[54:55] op_sel_hi:[1,0]
	v_pk_mul_f32 v[130:131], v[130:131], v[54:55] op_sel_hi:[1,0]
	v_pk_mul_f32 v[132:133], v[132:133], v[54:55] op_sel_hi:[1,0]
	s_waitcnt lgkmcnt(3)
	v_pk_mul_f32 v[126:127], v[126:127], v[56:57] op_sel_hi:[1,0]
	v_pk_mul_f32 v[128:129], v[128:129], v[56:57] op_sel_hi:[1,0]
	v_pk_mul_f32 v[122:123], v[122:123], v[56:57] op_sel_hi:[1,0]
	v_pk_mul_f32 v[124:125], v[124:125], v[56:57] op_sel_hi:[1,0]
	v_pk_mul_f32 v[118:119], v[118:119], v[56:57] op_sel_hi:[1,0]
	v_pk_mul_f32 v[120:121], v[120:121], v[56:57] op_sel_hi:[1,0]
	v_pk_mul_f32 v[114:115], v[114:115], v[56:57] op_sel_hi:[1,0]
	v_pk_mul_f32 v[116:117], v[116:117], v[56:57] op_sel_hi:[1,0]
	s_waitcnt lgkmcnt(2)
	v_pk_mul_f32 v[110:111], v[110:111], v[58:59] op_sel_hi:[1,0]
	v_pk_mul_f32 v[112:113], v[112:113], v[58:59] op_sel_hi:[1,0]
	v_pk_mul_f32 v[106:107], v[106:107], v[58:59] op_sel_hi:[1,0]
	v_pk_mul_f32 v[108:109], v[108:109], v[58:59] op_sel_hi:[1,0]
	v_pk_mul_f32 v[102:103], v[102:103], v[58:59] op_sel_hi:[1,0]
	v_pk_mul_f32 v[104:105], v[104:105], v[58:59] op_sel_hi:[1,0]
	v_pk_mul_f32 v[98:99], v[98:99], v[58:59] op_sel_hi:[1,0]
	v_pk_mul_f32 v[100:101], v[100:101], v[58:59] op_sel_hi:[1,0]
	s_waitcnt lgkmcnt(1)
	v_pk_mul_f32 v[94:95], v[94:95], v[60:61] op_sel_hi:[1,0]
	v_pk_mul_f32 v[96:97], v[96:97], v[60:61] op_sel_hi:[1,0]
	v_pk_mul_f32 v[90:91], v[90:91], v[60:61] op_sel_hi:[1,0]
	v_pk_mul_f32 v[92:93], v[92:93], v[60:61] op_sel_hi:[1,0]
	v_pk_mul_f32 v[86:87], v[86:87], v[60:61] op_sel_hi:[1,0]
	v_pk_mul_f32 v[88:89], v[88:89], v[60:61] op_sel_hi:[1,0]
	v_pk_mul_f32 v[82:83], v[82:83], v[60:61] op_sel_hi:[1,0]
	v_pk_mul_f32 v[84:85], v[84:85], v[60:61] op_sel_hi:[1,0]
	s_waitcnt lgkmcnt(0)
	v_pk_mul_f32 v[78:79], v[78:79], v[62:63] op_sel_hi:[1,0]
	v_pk_mul_f32 v[80:81], v[80:81], v[62:63] op_sel_hi:[1,0]
	v_pk_mul_f32 v[74:75], v[74:75], v[62:63] op_sel_hi:[1,0]
	v_pk_mul_f32 v[76:77], v[76:77], v[62:63] op_sel_hi:[1,0]
	v_pk_mul_f32 v[70:71], v[70:71], v[62:63] op_sel_hi:[1,0]
	v_pk_mul_f32 v[72:73], v[72:73], v[62:63] op_sel_hi:[1,0]
	v_pk_mul_f32 v[66:67], v[66:67], v[62:63] op_sel_hi:[1,0]
	v_pk_mul_f32 v[68:69], v[68:69], v[62:63] op_sel_hi:[1,0]
	s_cmp_eq_u64 s[22:23], 0
	s_cbranch_scc1 .Lqkv_plain
;     __device__ __forceinline__ void operator()(AccRef acc, const pg8::Unit& u, int wr, int wc, int fr, int fq) const {
;     ...
;                 float rs = 1.f;
;                 if (gain) {
;                     float ss = 0.f;
; #pragma unroll
;                     for (int bj = 0; bj < 2; ++bj)
; #pragma unroll
;                         for (int n = 0; n < 2; ++n) { const f32x4 x = xv[bj][n]; ss += (x[0] * x[0] + x[1] * x[1]) + (x[2] * x[2] + x[3] * x[3]); }
;                     ss += __shfl_xor(ss, 16); ss += __shfl_xor(ss, 32);
;                     rs = rsqrtf(ss * (1.0f / 64.0f) + RMS_EPS);
;                 }
; #pragma unroll
;                 for (int bj = 0; bj < 2; ++bj) {
;                     const f32x4 v0 = xv[bj][0] * rs * gv[bj][0], v1 = xv[bj][1] * rs * gv[bj][1];
	v_pk_mul_f32 v[24:25], v[190:191], v[190:191]
	v_pk_mul_f32 v[26:27], v[174:175], v[174:175]
	v_pk_mul_f32 v[28:29], v[158:159], v[158:159]
	v_pk_mul_f32 v[30:31], v[142:143], v[142:143]
	v_pk_mul_f32 v[32:33], v[126:127], v[126:127]
	v_pk_mul_f32 v[34:35], v[110:111], v[110:111]
	v_pk_mul_f32 v[36:37], v[94:95], v[94:95]
	v_pk_mul_f32 v[38:39], v[78:79], v[78:79]
	v_pk_fma_f32 v[24:25], v[192:193], v[192:193], v[24:25]
	v_pk_fma_f32 v[26:27], v[176:177], v[176:177], v[26:27]
	v_pk_fma_f32 v[28:29], v[160:161], v[160:161], v[28:29]
	v_pk_fma_f32 v[30:31], v[144:145], v[144:145], v[30:31]
	v_pk_fma_f32 v[32:33], v[128:129], v[128:129], v[32:33]
	v_pk_fma_f32 v[34:35], v[112:113], v[112:113], v[34:35]
	v_pk_fma_f32 v[36:37], v[96:97], v[96:97], v[36:37]
	v_pk_fma_f32 v[38:39], v[80:81], v[80:81], v[38:39]
	v_pk_fma_f32 v[24:25], v[186:187], v[186:187], v[24:25]
	v_pk_fma_f32 v[26:27], v[170:171], v[170:171], v[26:27]
	v_pk_fma_f32 v[28:29], v[154:155], v[154:155], v[28:29]
	v_pk_fma_f32 v[30:31], v[138:139], v[138:139], v[30:31]
	v_pk_fma_f32 v[32:33], v[122:123], v[122:123], v[32:33]
	v_pk_fma_f32 v[34:35], v[106:107], v[106:107], v[34:35]
	v_pk_fma_f32 v[36:37], v[90:91], v[90:91], v[36:37]
	v_pk_fma_f32 v[38:39], v[74:75], v[74:75], v[38:39]
	v_pk_fma_f32 v[24:25], v[188:189], v[188:189], v[24:25]
	v_pk_fma_f32 v[26:27], v[172:173], v[172:173], v[26:27]
	v_pk_fma_f32 v[28:29], v[156:157], v[156:157], v[28:29]
	v_pk_fma_f32 v[30:31], v[140:141], v[140:141], v[30:31]
	v_pk_fma_f32 v[32:33], v[124:125], v[124:125], v[32:33]
	v_pk_fma_f32 v[34:35], v[108:109], v[108:109], v[34:35]
	v_pk_fma_f32 v[36:37], v[92:93], v[92:93], v[36:37]
	v_pk_fma_f32 v[38:39], v[76:77], v[76:77], v[38:39]
	v_pk_fma_f32 v[24:25], v[182:183], v[182:183], v[24:25]
	v_pk_fma_f32 v[26:27], v[166:167], v[166:167], v[26:27]
	v_pk_fma_f32 v[28:29], v[150:151], v[150:151], v[28:29]
	v_pk_fma_f32 v[30:31], v[134:135], v[134:135], v[30:31]
	v_pk_fma_f32 v[32:33], v[118:119], v[118:119], v[32:33]
	v_pk_fma_f32 v[34:35], v[102:103], v[102:103], v[34:35]
	v_pk_fma_f32 v[36:37], v[86:87], v[86:87], v[36:37]
	v_pk_fma_f32 v[38:39], v[70:71], v[70:71], v[38:39]
	v_pk_fma_f32 v[24:25], v[184:185], v[184:185], v[24:25]
	v_pk_fma_f32 v[26:27], v[168:169], v[168:169], v[26:27]
	v_pk_fma_f32 v[28:29], v[152:153], v[152:153], v[28:29]
	v_pk_fma_f32 v[30:31], v[136:137], v[136:137], v[30:31]
	v_pk_fma_f32 v[32:33], v[120:121], v[120:121], v[32:33]
	v_pk_fma_f32 v[34:35], v[104:105], v[104:105], v[34:35]
	v_pk_fma_f32 v[36:37], v[88:89], v[88:89], v[36:37]
	v_pk_fma_f32 v[38:39], v[72:73], v[72:73], v[38:39]
	v_pk_fma_f32 v[24:25], v[178:179], v[178:179], v[24:25]
	v_pk_fma_f32 v[26:27], v[162:163], v[162:163], v[26:27]
	v_pk_fma_f32 v[28:29], v[146:147], v[146:147], v[28:29]
	v_pk_fma_f32 v[30:31], v[130:131], v[130:131], v[30:31]
	v_pk_fma_f32 v[32:33], v[114:115], v[114:115], v[32:33]
	v_pk_fma_f32 v[34:35], v[98:99], v[98:99], v[34:35]
	v_pk_fma_f32 v[36:37], v[82:83], v[82:83], v[36:37]
	v_pk_fma_f32 v[38:39], v[66:67], v[66:67], v[38:39]
	v_pk_fma_f32 v[24:25], v[180:181], v[180:181], v[24:25]
	v_pk_fma_f32 v[26:27], v[164:165], v[164:165], v[26:27]
	v_pk_fma_f32 v[28:29], v[148:149], v[148:149], v[28:29]
	v_pk_fma_f32 v[30:31], v[132:133], v[132:133], v[30:31]
	v_pk_fma_f32 v[32:33], v[116:117], v[116:117], v[32:33]
	v_pk_fma_f32 v[34:35], v[100:101], v[100:101], v[34:35]
	v_pk_fma_f32 v[36:37], v[84:85], v[84:85], v[36:37]
	v_pk_fma_f32 v[38:39], v[68:69], v[68:69], v[38:39]
	v_add_f32_e32 v49, v24, v25
	v_add_f32_e32 v51, v26, v27
	v_add_f32_e32 v53, v28, v29
	v_add_f32_e32 v55, v30, v31
	v_add_f32_e32 v57, v32, v33
	v_add_f32_e32 v59, v34, v35
	v_add_f32_e32 v61, v36, v37
	v_add_f32_e32 v63, v38, v39
	ds_bpermute_b32 v194, v40, v49
	ds_bpermute_b32 v195, v40, v51
	ds_bpermute_b32 v196, v40, v53
	ds_bpermute_b32 v197, v40, v55
	ds_bpermute_b32 v198, v40, v57
	ds_bpermute_b32 v199, v40, v59
	ds_bpermute_b32 v200, v40, v61
	ds_bpermute_b32 v201, v40, v63
	s_waitcnt lgkmcnt(7)
	v_add_f32_e32 v49, v49, v194
	ds_bpermute_b32 v202, v42, v49
	s_waitcnt lgkmcnt(7)
	v_add_f32_e32 v51, v51, v195
	ds_bpermute_b32 v203, v42, v51
	s_waitcnt lgkmcnt(7)
	v_add_f32_e32 v53, v53, v196
	ds_bpermute_b32 v204, v42, v53
	s_waitcnt lgkmcnt(7)
	v_add_f32_e32 v55, v55, v197
	ds_bpermute_b32 v205, v42, v55
	s_waitcnt lgkmcnt(7)
	v_add_f32_e32 v57, v57, v198
	ds_bpermute_b32 v206, v42, v57
	s_waitcnt lgkmcnt(7)
	v_add_f32_e32 v59, v59, v199
	ds_bpermute_b32 v207, v42, v59
	s_waitcnt lgkmcnt(7)
	v_add_f32_e32 v61, v61, v200
	ds_bpermute_b32 v208, v42, v61
	s_waitcnt lgkmcnt(7)
	v_add_f32_e32 v63, v63, v201
	ds_bpermute_b32 v209, v42, v63
	s_waitcnt vmcnt(0)
	v_pk_mul_f32 v[8:9], s[14:15], v[8:9] op_sel_hi:[0,1]
	v_pk_mul_f32 v[6:7], s[14:15], v[6:7] op_sel_hi:[0,1]
	v_pk_mul_f32 v[4:5], s[14:15], v[4:5] op_sel_hi:[0,1]
	v_pk_mul_f32 v[2:3], s[14:15], v[2:3] op_sel_hi:[0,1]
	v_pk_mul_f32 v[16:17], s[14:15], v[16:17] op_sel_hi:[0,1]
	v_pk_mul_f32 v[10:11], s[14:15], v[10:11] op_sel_hi:[0,1]
	v_pk_mul_f32 v[14:15], s[14:15], v[14:15] op_sel_hi:[0,1]
	v_pk_mul_f32 v[12:13], s[14:15], v[12:13] op_sel_hi:[0,1]
	s_waitcnt lgkmcnt(7)
	v_add_f32_e32 v49, v49, v202
	v_fmamk_f32 v49, v49, 0x3c800000, v215
	v_mul_f32_e32 v194, 0x4b800000, v49
	v_cmp_gt_f32_e32 vcc, s3, v49
	s_nop 1
	v_cndmask_b32_e32 v49, v49, v194, vcc
	v_rsq_f32_e32 v49, v49
	s_nop 0
	v_mul_f32_e32 v194, 0x45800000, v49
	v_cndmask_b32_e32 v48, v49, v194, vcc
	s_waitcnt lgkmcnt(6)
	v_add_f32_e32 v51, v51, v203
	v_fmamk_f32 v51, v51, 0x3c800000, v215
	v_mul_f32_e32 v195, 0x4b800000, v51
	v_cmp_gt_f32_e32 vcc, s3, v51
	s_nop 1
	v_cndmask_b32_e32 v51, v51, v195, vcc
	v_rsq_f32_e32 v51, v51
	s_nop 0
	v_mul_f32_e32 v195, 0x45800000, v51
	v_cndmask_b32_e32 v50, v51, v195, vcc
	s_waitcnt lgkmcnt(5)
; __device__ __forceinline__ unsigned pk2(float lo, float hi) { f32x2_t v = {lo, hi}; bf16x2_t b = __builtin_convertvector(v, bf16x2_t); return __builtin_bit_cast(unsigned, b); }
;     __device__ __forceinline__ void operator()(AccRef acc, const pg8::Unit& u, int wr, int wc, int fr, int fq) const {
;     ...
;                 float rs = 1.f;
;                 if (gain) {
;                     float ss = 0.f;
; #pragma unroll
;                     for (int bj = 0; bj < 2; ++bj)
; #pragma unroll
;                         for (int n = 0; n < 2; ++n) { const f32x4 x = xv[bj][n]; ss += (x[0] * x[0] + x[1] * x[1]) + (x[2] * x[2] + x[3] * x[3]); }
;                     ss += __shfl_xor(ss, 16); ss += __shfl_xor(ss, 32);
;                     rs = rsqrtf(ss * (1.0f / 64.0f) + RMS_EPS);
;                 }
; #pragma unroll
;                 for (int bj = 0; bj < 2; ++bj) {
;                     const f32x4 v0 = xv[bj][0] * rs * gv[bj][0], v1 = xv[bj][1] * rs * gv[bj][1];
;                     v4u w; w.x = pk2(v0[0], v0[1]); w.y = pk2(v0[2], v0[3]); w.z = pk2(v1[0], v1[1]); w.w = pk2(v1[2], v1[3]);
;                     *(v4u*)(dst + (size_t)row * pitch + 32 * bj) = w;
;                 }
	v_add_f32_e32 v53, v53, v204
	v_fmamk_f32 v53, v53, 0x3c800000, v215
	v_mul_f32_e32 v196, 0x4b800000, v53
	v_cmp_gt_f32_e32 vcc, s3, v53
	s_nop 1
	v_cndmask_b32_e32 v53, v53, v196, vcc
	v_rsq_f32_e32 v53, v53
	s_nop 0
	v_mul_f32_e32 v196, 0x45800000, v53
	v_cndmask_b32_e32 v52, v53, v196, vcc
	s_waitcnt lgkmcnt(4)
	v_add_f32_e32 v55, v55, v205
	v_fmamk_f32 v55, v55, 0x3c800000, v215
	v_mul_f32_e32 v197, 0x4b800000, v55
	v_cmp_gt_f32_e32 vcc, s3, v55
	s_nop 1
	v_cndmask_b32_e32 v55, v55, v197, vcc
	v_rsq_f32_e32 v55, v55
	s_nop 0
	v_mul_f32_e32 v197, 0x45800000, v55
	v_cndmask_b32_e32 v54, v55, v197, vcc
	s_waitcnt lgkmcnt(3)
	v_add_f32_e32 v57, v57, v206
	v_fmamk_f32 v57, v57, 0x3c800000, v215
	v_mul_f32_e32 v198, 0x4b800000, v57
	v_cmp_gt_f32_e32 vcc, s3, v57
	s_nop 1
	v_cndmask_b32_e32 v57, v57, v198, vcc
	v_rsq_f32_e32 v57, v57
	s_nop 0
	v_mul_f32_e32 v198, 0x45800000, v57
	v_cndmask_b32_e32 v56, v57, v198, vcc
	s_waitcnt lgkmcnt(2)
	v_add_f32_e32 v59, v59, v207
	v_fmamk_f32 v59, v59, 0x3c800000, v215
	v_mul_f32_e32 v199, 0x4b800000, v59
	v_cmp_gt_f32_e32 vcc, s3, v59
	s_nop 1
	v_cndmask_b32_e32 v59, v59, v199, vcc
	v_rsq_f32_e32 v59, v59
	s_nop 0
	v_mul_f32_e32 v199, 0x45800000, v59
	v_cndmask_b32_e32 v58, v59, v199, vcc
	s_waitcnt lgkmcnt(1)
	v_add_f32_e32 v61, v61, v208
	v_fmamk_f32 v61, v61, 0x3c800000, v215
	v_mul_f32_e32 v200, 0x4b800000, v61
	v_cmp_gt_f32_e32 vcc, s3, v61
	s_nop 1
	v_cndmask_b32_e32 v61, v61, v200, vcc
	v_rsq_f32_e32 v61, v61
	s_nop 0
	v_mul_f32_e32 v200, 0x45800000, v61
	v_cndmask_b32_e32 v60, v61, v200, vcc
	s_waitcnt lgkmcnt(0)
	v_add_f32_e32 v63, v63, v209
	v_fmamk_f32 v63, v63, 0x3c800000, v215
	v_mul_f32_e32 v201, 0x4b800000, v63
	v_cmp_gt_f32_e32 vcc, s3, v63
	s_nop 1
	v_cndmask_b32_e32 v63, v63, v201, vcc
	v_rsq_f32_e32 v63, v63
	s_nop 0
	v_mul_f32_e32 v201, 0x45800000, v63
	v_cndmask_b32_e32 v62, v63, v201, vcc
	v_pk_mul_f32 v[190:191], v[190:191], v[48:49] op_sel_hi:[1,0]
	v_pk_mul_f32 v[192:193], v[192:193], v[48:49] op_sel_hi:[1,0]
	v_pk_mul_f32 v[186:187], v[186:187], v[48:49] op_sel_hi:[1,0]
	v_pk_mul_f32 v[188:189], v[188:189], v[48:49] op_sel_hi:[1,0]
	v_pk_mul_f32 v[182:183], v[182:183], v[48:49] op_sel_hi:[1,0]
	v_pk_mul_f32 v[184:185], v[184:185], v[48:49] op_sel_hi:[1,0]
	v_pk_mul_f32 v[178:179], v[178:179], v[48:49] op_sel_hi:[1,0]
	v_pk_mul_f32 v[180:181], v[180:181], v[48:49] op_sel_hi:[1,0]
	v_pk_mul_f32 v[190:191], v[2:3], v[190:191]
	v_pk_mul_f32 v[192:193], v[4:5], v[192:193]
	v_pk_mul_f32 v[186:187], v[6:7], v[186:187]
	v_pk_mul_f32 v[188:189], v[8:9], v[188:189]
	v_pk_mul_f32 v[182:183], v[10:11], v[182:183]
	v_pk_mul_f32 v[184:185], v[12:13], v[184:185]
	v_pk_mul_f32 v[178:179], v[14:15], v[178:179]
	v_pk_mul_f32 v[180:181], v[16:17], v[180:181]
	v_cvt_pk_bf16_f32 v190, v190, v191
	v_cvt_pk_bf16_f32 v191, v192, v193
	v_cvt_pk_bf16_f32 v192, v186, v187
	v_cvt_pk_bf16_f32 v193, v188, v189
	global_store_dwordx4 v22, v[190:193], s[12:13]
	v_cvt_pk_bf16_f32 v182, v182, v183
	v_cvt_pk_bf16_f32 v183, v184, v185
	v_cvt_pk_bf16_f32 v184, v178, v179
	v_cvt_pk_bf16_f32 v185, v180, v181
	global_store_dwordx4 v22, v[182:185], s[12:13] offset:64
	s_add_u32 s12, s12, s20
	s_addc_u32 s13, s13, 0
	v_pk_mul_f32 v[174:175], v[174:175], v[50:51] op_sel_hi:[1,0]
	v_pk_mul_f32 v[176:177], v[176:177], v[50:51] op_sel_hi:[1,0]
	v_pk_mul_f32 v[170:171], v[170:171], v[50:51] op_sel_hi:[1,0]
	v_pk_mul_f32 v[172:173], v[172:173], v[50:51] op_sel_hi:[1,0]
	v_pk_mul_f32 v[166:167], v[166:167], v[50:51] op_sel_hi:[1,0]
	v_pk_mul_f32 v[168:169], v[168:169], v[50:51] op_sel_hi:[1,0]
	v_pk_mul_f32 v[162:163], v[162:163], v[50:51] op_sel_hi:[1,0]
	v_pk_mul_f32 v[164:165], v[164:165], v[50:51] op_sel_hi:[1,0]
	v_pk_mul_f32 v[174:175], v[2:3], v[174:175]
	v_pk_mul_f32 v[176:177], v[4:5], v[176:177]
	v_pk_mul_f32 v[170:171], v[6:7], v[170:171]
	v_pk_mul_f32 v[172:173], v[8:9], v[172:173]
	v_pk_mul_f32 v[166:167], v[10:11], v[166:167]
	v_pk_mul_f32 v[168:169], v[12:13], v[168:169]
	v_pk_mul_f32 v[162:163], v[14:15], v[162:163]
	v_pk_mul_f32 v[164:165], v[16:17], v[164:165]
	v_cvt_pk_bf16_f32 v174, v174, v175
	v_cvt_pk_bf16_f32 v175, v176, v177
	v_cvt_pk_bf16_f32 v176, v170, v171
	v_cvt_pk_bf16_f32 v177, v172, v173
	global_store_dwordx4 v22, v[174:177], s[12:13]
	v_cvt_pk_bf16_f32 v166, v166, v167
	v_cvt_pk_bf16_f32 v167, v168, v169
	v_cvt_pk_bf16_f32 v168, v162, v163
	v_cvt_pk_bf16_f32 v169, v164, v165
	global_store_dwordx4 v22, v[166:169], s[12:13] offset:64
	s_add_u32 s12, s12, s20
	s_addc_u32 s13, s13, 0
	v_pk_mul_f32 v[158:159], v[158:159], v[52:53] op_sel_hi:[1,0]
	v_pk_mul_f32 v[160:161], v[160:161], v[52:53] op_sel_hi:[1,0]
	v_pk_mul_f32 v[154:155], v[154:155], v[52:53] op_sel_hi:[1,0]
	v_pk_mul_f32 v[156:157], v[156:157], v[52:53] op_sel_hi:[1,0]
	v_pk_mul_f32 v[150:151], v[150:151], v[52:53] op_sel_hi:[1,0]
	v_pk_mul_f32 v[152:153], v[152:153], v[52:53] op_sel_hi:[1,0]
	v_pk_mul_f32 v[146:147], v[146:147], v[52:53] op_sel_hi:[1,0]
	v_pk_mul_f32 v[148:149], v[148:149], v[52:53] op_sel_hi:[1,0]
	v_pk_mul_f32 v[158:159], v[2:3], v[158:159]
	v_pk_mul_f32 v[160:161], v[4:5], v[160:161]
	v_pk_mul_f32 v[154:155], v[6:7], v[154:155]
	v_pk_mul_f32 v[156:157], v[8:9], v[156:157]
	v_pk_mul_f32 v[150:151], v[10:11], v[150:151]
	v_pk_mul_f32 v[152:153], v[12:13], v[152:153]
	v_pk_mul_f32 v[146:147], v[14:15], v[146:147]
	v_pk_mul_f32 v[148:149], v[16:17], v[148:149]
	v_cvt_pk_bf16_f32 v158, v158, v159
	v_cvt_pk_bf16_f32 v159, v160, v161
	v_cvt_pk_bf16_f32 v160, v154, v155
	v_cvt_pk_bf16_f32 v161, v156, v157
	global_store_dwordx4 v22, v[158:161], s[12:13]
	v_cvt_pk_bf16_f32 v150, v150, v151
	v_cvt_pk_bf16_f32 v151, v152, v153
; __device__ __forceinline__ unsigned pk2(float lo, float hi) { f32x2_t v = {lo, hi}; bf16x2_t b = __builtin_convertvector(v, bf16x2_t); return __builtin_bit_cast(unsigned, b); }
;     __device__ __forceinline__ void operator()(AccRef acc, const pg8::Unit& u, int wr, int wc, int fr, int fq) const {
;     ...
; #pragma unroll
;                 for (int bj = 0; bj < 2; ++bj) {
;                     const f32x4 v0 = xv[bj][0] * rs * gv[bj][0], v1 = xv[bj][1] * rs * gv[bj][1];
;                     v4u w; w.x = pk2(v0[0], v0[1]); w.y = pk2(v0[2], v0[3]); w.z = pk2(v1[0], v1[1]); w.w = pk2(v1[2], v1[3]);
;                     *(v4u*)(dst + (size_t)row * pitch + 32 * bj) = w;
;                 }
	v_cvt_pk_bf16_f32 v152, v146, v147
	v_cvt_pk_bf16_f32 v153, v148, v149
	global_store_dwordx4 v22, v[150:153], s[12:13] offset:64
	s_add_u32 s12, s12, s20
	s_addc_u32 s13, s13, 0
	v_pk_mul_f32 v[142:143], v[142:143], v[54:55] op_sel_hi:[1,0]
	v_pk_mul_f32 v[144:145], v[144:145], v[54:55] op_sel_hi:[1,0]
	v_pk_mul_f32 v[138:139], v[138:139], v[54:55] op_sel_hi:[1,0]
	v_pk_mul_f32 v[140:141], v[140:141], v[54:55] op_sel_hi:[1,0]
	v_pk_mul_f32 v[134:135], v[134:135], v[54:55] op_sel_hi:[1,0]
	v_pk_mul_f32 v[136:137], v[136:137], v[54:55] op_sel_hi:[1,0]
	v_pk_mul_f32 v[130:131], v[130:131], v[54:55] op_sel_hi:[1,0]
	v_pk_mul_f32 v[132:133], v[132:133], v[54:55] op_sel_hi:[1,0]
	v_pk_mul_f32 v[142:143], v[2:3], v[142:143]
	v_pk_mul_f32 v[144:145], v[4:5], v[144:145]
	v_pk_mul_f32 v[138:139], v[6:7], v[138:139]
	v_pk_mul_f32 v[140:141], v[8:9], v[140:141]
	v_pk_mul_f32 v[134:135], v[10:11], v[134:135]
	v_pk_mul_f32 v[136:137], v[12:13], v[136:137]
	v_pk_mul_f32 v[130:131], v[14:15], v[130:131]
	v_pk_mul_f32 v[132:133], v[16:17], v[132:133]
	v_cvt_pk_bf16_f32 v142, v142, v143
	v_cvt_pk_bf16_f32 v143, v144, v145
	v_cvt_pk_bf16_f32 v144, v138, v139
	v_cvt_pk_bf16_f32 v145, v140, v141
	global_store_dwordx4 v22, v[142:145], s[12:13]
	v_cvt_pk_bf16_f32 v134, v134, v135
	v_cvt_pk_bf16_f32 v135, v136, v137
	v_cvt_pk_bf16_f32 v136, v130, v131
	v_cvt_pk_bf16_f32 v137, v132, v133
	global_store_dwordx4 v22, v[134:137], s[12:13] offset:64
	s_add_u32 s12, s12, s21
	s_addc_u32 s13, s13, 0
	v_pk_mul_f32 v[126:127], v[126:127], v[56:57] op_sel_hi:[1,0]
	v_pk_mul_f32 v[128:129], v[128:129], v[56:57] op_sel_hi:[1,0]
	v_pk_mul_f32 v[122:123], v[122:123], v[56:57] op_sel_hi:[1,0]
	v_pk_mul_f32 v[124:125], v[124:125], v[56:57] op_sel_hi:[1,0]
	v_pk_mul_f32 v[118:119], v[118:119], v[56:57] op_sel_hi:[1,0]
	v_pk_mul_f32 v[120:121], v[120:121], v[56:57] op_sel_hi:[1,0]
	v_pk_mul_f32 v[114:115], v[114:115], v[56:57] op_sel_hi:[1,0]
	v_pk_mul_f32 v[116:117], v[116:117], v[56:57] op_sel_hi:[1,0]
	v_pk_mul_f32 v[126:127], v[2:3], v[126:127]
	v_pk_mul_f32 v[128:129], v[4:5], v[128:129]
	v_pk_mul_f32 v[122:123], v[6:7], v[122:123]
	v_pk_mul_f32 v[124:125], v[8:9], v[124:125]
	v_pk_mul_f32 v[118:119], v[10:11], v[118:119]
	v_pk_mul_f32 v[120:121], v[12:13], v[120:121]
	v_pk_mul_f32 v[114:115], v[14:15], v[114:115]
	v_pk_mul_f32 v[116:117], v[16:17], v[116:117]
	v_cvt_pk_bf16_f32 v126, v126, v127
	v_cvt_pk_bf16_f32 v127, v128, v129
	v_cvt_pk_bf16_f32 v128, v122, v123
	v_cvt_pk_bf16_f32 v129, v124, v125
	global_store_dwordx4 v22, v[126:129], s[12:13]
	v_cvt_pk_bf16_f32 v118, v118, v119
	v_cvt_pk_bf16_f32 v119, v120, v121
	v_cvt_pk_bf16_f32 v120, v114, v115
	v_cvt_pk_bf16_f32 v121, v116, v117
	global_store_dwordx4 v22, v[118:121], s[12:13] offset:64
	s_add_u32 s12, s12, s20
	s_addc_u32 s13, s13, 0
	v_pk_mul_f32 v[110:111], v[110:111], v[58:59] op_sel_hi:[1,0]
	v_pk_mul_f32 v[112:113], v[112:113], v[58:59] op_sel_hi:[1,0]
	v_pk_mul_f32 v[106:107], v[106:107], v[58:59] op_sel_hi:[1,0]
	v_pk_mul_f32 v[108:109], v[108:109], v[58:59] op_sel_hi:[1,0]
	v_pk_mul_f32 v[102:103], v[102:103], v[58:59] op_sel_hi:[1,0]
	v_pk_mul_f32 v[104:105], v[104:105], v[58:59] op_sel_hi:[1,0]
	v_pk_mul_f32 v[98:99], v[98:99], v[58:59] op_sel_hi:[1,0]
	v_pk_mul_f32 v[100:101], v[100:101], v[58:59] op_sel_hi:[1,0]
	v_pk_mul_f32 v[110:111], v[2:3], v[110:111]
	v_pk_mul_f32 v[112:113], v[4:5], v[112:113]
	v_pk_mul_f32 v[106:107], v[6:7], v[106:107]
	v_pk_mul_f32 v[108:109], v[8:9], v[108:109]
	v_pk_mul_f32 v[102:103], v[10:11], v[102:103]
	v_pk_mul_f32 v[104:105], v[12:13], v[104:105]
	v_pk_mul_f32 v[98:99], v[14:15], v[98:99]
	v_pk_mul_f32 v[100:101], v[16:17], v[100:101]
	v_cvt_pk_bf16_f32 v110, v110, v111
	v_cvt_pk_bf16_f32 v111, v112, v113
	v_cvt_pk_bf16_f32 v112, v106, v107
	v_cvt_pk_bf16_f32 v113, v108, v109
	global_store_dwordx4 v22, v[110:113], s[12:13]
	v_cvt_pk_bf16_f32 v102, v102, v103
	v_cvt_pk_bf16_f32 v103, v104, v105
	v_cvt_pk_bf16_f32 v104, v98, v99
	v_cvt_pk_bf16_f32 v105, v100, v101
	global_store_dwordx4 v22, v[102:105], s[12:13] offset:64
	s_add_u32 s12, s12, s20
	s_addc_u32 s13, s13, 0
	v_pk_mul_f32 v[94:95], v[94:95], v[60:61] op_sel_hi:[1,0]
	v_pk_mul_f32 v[96:97], v[96:97], v[60:61] op_sel_hi:[1,0]
	v_pk_mul_f32 v[90:91], v[90:91], v[60:61] op_sel_hi:[1,0]
	v_pk_mul_f32 v[92:93], v[92:93], v[60:61] op_sel_hi:[1,0]
	v_pk_mul_f32 v[86:87], v[86:87], v[60:61] op_sel_hi:[1,0]
	v_pk_mul_f32 v[88:89], v[88:89], v[60:61] op_sel_hi:[1,0]
	v_pk_mul_f32 v[82:83], v[82:83], v[60:61] op_sel_hi:[1,0]
	v_pk_mul_f32 v[84:85], v[84:85], v[60:61] op_sel_hi:[1,0]
	v_pk_mul_f32 v[94:95], v[2:3], v[94:95]
	v_pk_mul_f32 v[96:97], v[4:5], v[96:97]
	v_pk_mul_f32 v[90:91], v[6:7], v[90:91]
	v_pk_mul_f32 v[92:93], v[8:9], v[92:93]
	v_pk_mul_f32 v[86:87], v[10:11], v[86:87]
	v_pk_mul_f32 v[88:89], v[12:13], v[88:89]
	v_pk_mul_f32 v[82:83], v[14:15], v[82:83]
	v_pk_mul_f32 v[84:85], v[16:17], v[84:85]
	v_cvt_pk_bf16_f32 v94, v94, v95
	v_cvt_pk_bf16_f32 v95, v96, v97
	v_cvt_pk_bf16_f32 v96, v90, v91
	v_cvt_pk_bf16_f32 v97, v92, v93
	global_store_dwordx4 v22, v[94:97], s[12:13]
	v_cvt_pk_bf16_f32 v86, v86, v87
	v_cvt_pk_bf16_f32 v87, v88, v89
	v_cvt_pk_bf16_f32 v88, v82, v83
	v_cvt_pk_bf16_f32 v89, v84, v85
	global_store_dwordx4 v22, v[86:89], s[12:13] offset:64
	s_add_u32 s12, s12, s20
	s_addc_u32 s13, s13, 0
	v_pk_mul_f32 v[78:79], v[78:79], v[62:63] op_sel_hi:[1,0]
	v_pk_mul_f32 v[80:81], v[80:81], v[62:63] op_sel_hi:[1,0]
	v_pk_mul_f32 v[74:75], v[74:75], v[62:63] op_sel_hi:[1,0]
	v_pk_mul_f32 v[76:77], v[76:77], v[62:63] op_sel_hi:[1,0]
	v_pk_mul_f32 v[70:71], v[70:71], v[62:63] op_sel_hi:[1,0]
	v_pk_mul_f32 v[72:73], v[72:73], v[62:63] op_sel_hi:[1,0]
	v_pk_mul_f32 v[66:67], v[66:67], v[62:63] op_sel_hi:[1,0]
	v_pk_mul_f32 v[68:69], v[68:69], v[62:63] op_sel_hi:[1,0]
	v_pk_mul_f32 v[78:79], v[2:3], v[78:79]
	v_pk_mul_f32 v[80:81], v[4:5], v[80:81]
	v_pk_mul_f32 v[74:75], v[6:7], v[74:75]
	v_pk_mul_f32 v[76:77], v[8:9], v[76:77]
	v_pk_mul_f32 v[70:71], v[10:11], v[70:71]
	v_pk_mul_f32 v[72:73], v[12:13], v[72:73]
	v_pk_mul_f32 v[66:67], v[14:15], v[66:67]
	v_pk_mul_f32 v[68:69], v[16:17], v[68:69]
	v_cvt_pk_bf16_f32 v78, v78, v79
	v_cvt_pk_bf16_f32 v79, v80, v81
	v_cvt_pk_bf16_f32 v80, v74, v75
	v_cvt_pk_bf16_f32 v81, v76, v77
	global_store_dwordx4 v22, v[78:81], s[12:13]
	v_cvt_pk_bf16_f32 v70, v70, v71
	v_cvt_pk_bf16_f32 v71, v72, v73
	v_cvt_pk_bf16_f32 v72, v66, v67
	v_cvt_pk_bf16_f32 v73, v68, v69
	global_store_dwordx4 v22, v[70:73], s[12:13] offset:64
	s_branch .Lqkv_done
; __device__ __forceinline__ unsigned pk2(float lo, float hi) { f32x2_t v = {lo, hi}; bf16x2_t b = __builtin_convertvector(v, bf16x2_t); return __builtin_bit_cast(unsigned, b); }
;     __device__ __forceinline__ void operator()(AccRef acc, const pg8::Unit& u, int wr, int wc, int fr, int fq) const {
;     ...
;         size_t off; int pitch, lg; const float* gain = nullptr; float sc = 1.f;
;         if (G < 8)       { off = B_QA; pitch = 512; lg = G;      gain = aq; sc = QSCALE; }
;         else if (G < 16) { off = B_KA; pitch = 512; lg = G - 8;  gain = ak; }
;         else if (G < 24) { off = B_VA; pitch = 512; lg = G - 16; }
;         else if (G < 30) { off = B_QB; pitch = 384; lg = G - 24; sc = QSCALE; }
;         else if (G < 36) { off = B_KB; pitch = 384; lg = G - 30; }
;         else if (G < 42) { off = B_VB; pitch = 384; lg = G - 36; }
;         else if (G < 48) { off = B_QC; pitch = 384; lg = G - 42; gain = cq; sc = QSCALE; }
;         else if (G < 54) { off = B_KC; pitch = 384; lg = G - 48; gain = ck; }
;         else if (G < 60) { off = B_VC; pitch = 384; lg = G - 54; }
;         else if (G < 66) { off = B_QD; pitch = 384; lg = G - 60; gain = dq; sc = QSCALE; }
;         else if (G < 72) { off = B_KD; pitch = 384; lg = G - 66; gain = dk; }
;         else             { off = B_VD; pitch = 384; lg = G - 72; }
;         bf16* dst = (bf16*)(big + off) + lg * 64 + 8 * fq;
;         f32x4 gv[2][2];
; #pragma unroll
;         for (int bj = 0; bj < 2; ++bj)
; #pragma unroll
;             for (int n = 0; n < 2; ++n) {
;                 f32x4 g4 = {1.f, 1.f, 1.f, 1.f};
;                 if (gain) g4 = *(const f32x4*)(gain + 32 * bj + 8 * fq + 4 * n);
;                 gv[bj][n] = g4 * sc;
;             }
;     ...
; #pragma unroll
;                 for (int bj = 0; bj < 2; ++bj) {
;                     const f32x4 v0 = xv[bj][0] * rs * gv[bj][0], v1 = xv[bj][1] * rs * gv[bj][1];
;                     v4u w; w.x = pk2(v0[0], v0[1]); w.y = pk2(v0[2], v0[3]); w.z = pk2(v1[0], v1[1]); w.w = pk2(v1[2], v1[3]);
;                     *(v4u*)(dst + (size_t)row * pitch + 32 * bj) = w;
;                 }
.Lqkv_plain:
	v_pk_mul_f32 v[190:191], s[14:15], v[190:191] op_sel_hi:[0,1]
	v_pk_mul_f32 v[192:193], s[14:15], v[192:193] op_sel_hi:[0,1]
	v_pk_mul_f32 v[186:187], s[14:15], v[186:187] op_sel_hi:[0,1]
	v_pk_mul_f32 v[188:189], s[14:15], v[188:189] op_sel_hi:[0,1]
	v_pk_mul_f32 v[182:183], s[14:15], v[182:183] op_sel_hi:[0,1]
	v_pk_mul_f32 v[184:185], s[14:15], v[184:185] op_sel_hi:[0,1]
	v_pk_mul_f32 v[178:179], s[14:15], v[178:179] op_sel_hi:[0,1]
	v_pk_mul_f32 v[180:181], s[14:15], v[180:181] op_sel_hi:[0,1]
	v_cvt_pk_bf16_f32 v190, v190, v191
	v_cvt_pk_bf16_f32 v191, v192, v193
	v_cvt_pk_bf16_f32 v192, v186, v187
	v_cvt_pk_bf16_f32 v193, v188, v189
	global_store_dwordx4 v22, v[190:193], s[12:13]
	v_cvt_pk_bf16_f32 v182, v182, v183
	v_cvt_pk_bf16_f32 v183, v184, v185
	v_cvt_pk_bf16_f32 v184, v178, v179
	v_cvt_pk_bf16_f32 v185, v180, v181
	global_store_dwordx4 v22, v[182:185], s[12:13] offset:64
	s_add_u32 s12, s12, s20
	s_addc_u32 s13, s13, 0
	v_pk_mul_f32 v[174:175], s[14:15], v[174:175] op_sel_hi:[0,1]
	v_pk_mul_f32 v[176:177], s[14:15], v[176:177] op_sel_hi:[0,1]
	v_pk_mul_f32 v[170:171], s[14:15], v[170:171] op_sel_hi:[0,1]
	v_pk_mul_f32 v[172:173], s[14:15], v[172:173] op_sel_hi:[0,1]
	v_pk_mul_f32 v[166:167], s[14:15], v[166:167] op_sel_hi:[0,1]
	v_pk_mul_f32 v[168:169], s[14:15], v[168:169] op_sel_hi:[0,1]
	v_pk_mul_f32 v[162:163], s[14:15], v[162:163] op_sel_hi:[0,1]
	v_pk_mul_f32 v[164:165], s[14:15], v[164:165] op_sel_hi:[0,1]
	v_cvt_pk_bf16_f32 v174, v174, v175
	v_cvt_pk_bf16_f32 v175, v176, v177
	v_cvt_pk_bf16_f32 v176, v170, v171
	v_cvt_pk_bf16_f32 v177, v172, v173
	global_store_dwordx4 v22, v[174:177], s[12:13]
	v_cvt_pk_bf16_f32 v166, v166, v167
	v_cvt_pk_bf16_f32 v167, v168, v169
	v_cvt_pk_bf16_f32 v168, v162, v163
	v_cvt_pk_bf16_f32 v169, v164, v165
	global_store_dwordx4 v22, v[166:169], s[12:13] offset:64
	s_add_u32 s12, s12, s20
	s_addc_u32 s13, s13, 0
	v_pk_mul_f32 v[158:159], s[14:15], v[158:159] op_sel_hi:[0,1]
	v_pk_mul_f32 v[160:161], s[14:15], v[160:161] op_sel_hi:[0,1]
	v_pk_mul_f32 v[154:155], s[14:15], v[154:155] op_sel_hi:[0,1]
	v_pk_mul_f32 v[156:157], s[14:15], v[156:157] op_sel_hi:[0,1]
	v_pk_mul_f32 v[150:151], s[14:15], v[150:151] op_sel_hi:[0,1]
	v_pk_mul_f32 v[152:153], s[14:15], v[152:153] op_sel_hi:[0,1]
	v_pk_mul_f32 v[146:147], s[14:15], v[146:147] op_sel_hi:[0,1]
	v_pk_mul_f32 v[148:149], s[14:15], v[148:149] op_sel_hi:[0,1]
	v_cvt_pk_bf16_f32 v158, v158, v159
	v_cvt_pk_bf16_f32 v159, v160, v161
	v_cvt_pk_bf16_f32 v160, v154, v155
	v_cvt_pk_bf16_f32 v161, v156, v157
	global_store_dwordx4 v22, v[158:161], s[12:13]
	v_cvt_pk_bf16_f32 v150, v150, v151
	v_cvt_pk_bf16_f32 v151, v152, v153
	v_cvt_pk_bf16_f32 v152, v146, v147
	v_cvt_pk_bf16_f32 v153, v148, v149
	global_store_dwordx4 v22, v[150:153], s[12:13] offset:64
	s_add_u32 s12, s12, s20
	s_addc_u32 s13, s13, 0
	v_pk_mul_f32 v[142:143], s[14:15], v[142:143] op_sel_hi:[0,1]
	v_pk_mul_f32 v[144:145], s[14:15], v[144:145] op_sel_hi:[0,1]
	v_pk_mul_f32 v[138:139], s[14:15], v[138:139] op_sel_hi:[0,1]
	v_pk_mul_f32 v[140:141], s[14:15], v[140:141] op_sel_hi:[0,1]
	v_pk_mul_f32 v[134:135], s[14:15], v[134:135] op_sel_hi:[0,1]
	v_pk_mul_f32 v[136:137], s[14:15], v[136:137] op_sel_hi:[0,1]
	v_pk_mul_f32 v[130:131], s[14:15], v[130:131] op_sel_hi:[0,1]
	v_pk_mul_f32 v[132:133], s[14:15], v[132:133] op_sel_hi:[0,1]
	v_cvt_pk_bf16_f32 v142, v142, v143
	v_cvt_pk_bf16_f32 v143, v144, v145
	v_cvt_pk_bf16_f32 v144, v138, v139
	v_cvt_pk_bf16_f32 v145, v140, v141
	global_store_dwordx4 v22, v[142:145], s[12:13]
	v_cvt_pk_bf16_f32 v134, v134, v135
	v_cvt_pk_bf16_f32 v135, v136, v137
	v_cvt_pk_bf16_f32 v136, v130, v131
	v_cvt_pk_bf16_f32 v137, v132, v133
	global_store_dwordx4 v22, v[134:137], s[12:13] offset:64
	s_add_u32 s12, s12, s21
	s_addc_u32 s13, s13, 0
	v_pk_mul_f32 v[126:127], s[14:15], v[126:127] op_sel_hi:[0,1]
	v_pk_mul_f32 v[128:129], s[14:15], v[128:129] op_sel_hi:[0,1]
	v_pk_mul_f32 v[122:123], s[14:15], v[122:123] op_sel_hi:[0,1]
	v_pk_mul_f32 v[124:125], s[14:15], v[124:125] op_sel_hi:[0,1]
	v_pk_mul_f32 v[118:119], s[14:15], v[118:119] op_sel_hi:[0,1]
	v_pk_mul_f32 v[120:121], s[14:15], v[120:121] op_sel_hi:[0,1]
	v_pk_mul_f32 v[114:115], s[14:15], v[114:115] op_sel_hi:[0,1]
	v_pk_mul_f32 v[116:117], s[14:15], v[116:117] op_sel_hi:[0,1]
	v_cvt_pk_bf16_f32 v126, v126, v127
	v_cvt_pk_bf16_f32 v127, v128, v129
	v_cvt_pk_bf16_f32 v128, v122, v123
	v_cvt_pk_bf16_f32 v129, v124, v125
	global_store_dwordx4 v22, v[126:129], s[12:13]
	v_cvt_pk_bf16_f32 v118, v118, v119
	v_cvt_pk_bf16_f32 v119, v120, v121
	v_cvt_pk_bf16_f32 v120, v114, v115
	v_cvt_pk_bf16_f32 v121, v116, v117
	global_store_dwordx4 v22, v[118:121], s[12:13] offset:64
	s_add_u32 s12, s12, s20
	s_addc_u32 s13, s13, 0
	v_pk_mul_f32 v[110:111], s[14:15], v[110:111] op_sel_hi:[0,1]
	v_pk_mul_f32 v[112:113], s[14:15], v[112:113] op_sel_hi:[0,1]
	v_pk_mul_f32 v[106:107], s[14:15], v[106:107] op_sel_hi:[0,1]
	v_pk_mul_f32 v[108:109], s[14:15], v[108:109] op_sel_hi:[0,1]
	v_pk_mul_f32 v[102:103], s[14:15], v[102:103] op_sel_hi:[0,1]
	v_pk_mul_f32 v[104:105], s[14:15], v[104:105] op_sel_hi:[0,1]
	v_pk_mul_f32 v[98:99], s[14:15], v[98:99] op_sel_hi:[0,1]
	v_pk_mul_f32 v[100:101], s[14:15], v[100:101] op_sel_hi:[0,1]
	v_cvt_pk_bf16_f32 v110, v110, v111
	v_cvt_pk_bf16_f32 v111, v112, v113
	v_cvt_pk_bf16_f32 v112, v106, v107
	v_cvt_pk_bf16_f32 v113, v108, v109
	global_store_dwordx4 v22, v[110:113], s[12:13]
	v_cvt_pk_bf16_f32 v102, v102, v103
	v_cvt_pk_bf16_f32 v103, v104, v105
	v_cvt_pk_bf16_f32 v104, v98, v99
	v_cvt_pk_bf16_f32 v105, v100, v101
	global_store_dwordx4 v22, v[102:105], s[12:13] offset:64
; __device__ __forceinline__ unsigned pk2(float lo, float hi) { f32x2_t v = {lo, hi}; bf16x2_t b = __builtin_convertvector(v, bf16x2_t); return __builtin_bit_cast(unsigned, b); }
; __device__ __forceinline__ float fexp2(float x) { return __builtin_amdgcn_exp2f(x); }
; __device__ __forceinline__ float flog2(float x) { return __builtin_amdgcn_logf(x); }
;     __device__ __forceinline__ void operator()(AccRef acc, const pg8::Unit& u, int wr, int wc, int fr, int fq) const {
;     ...
;         if (G == 78) {
;             if (fq == 0) {
; #pragma unroll
;                 for (int ai = 0; ai < 2; ++ai)
; #pragma unroll
;                     for (int m = 0; m < 4; ++m) {
;                         const int row = row0 + ai * 128 + m * 16;
;                         const float rsr = rst[row & 255];
; #pragma unroll
;                         for (int e = 0; e < 6; ++e) {
;                             const float x = acc[ai][0][m][e >> 2][e & 3] * rsr + fb[e];
;                             const float ls = fminf(x, 0.f) - LN2 * flog2(1.0f + fexp2(-fabsf(x) * LOG2E));
;                             logf[(size_t)row * 8 + e] = ls;
;                         }
;                     }
;             }
;     ...
; #pragma unroll
;                 for (int bj = 0; bj < 2; ++bj) {
;                     const f32x4 v0 = xv[bj][0] * rs * gv[bj][0], v1 = xv[bj][1] * rs * gv[bj][1];
;                     v4u w; w.x = pk2(v0[0], v0[1]); w.y = pk2(v0[2], v0[3]); w.z = pk2(v1[0], v1[1]); w.w = pk2(v1[2], v1[3]);
;                     *(v4u*)(dst + (size_t)row * pitch + 32 * bj) = w;
;                 }
	s_add_u32 s12, s12, s20
	s_addc_u32 s13, s13, 0
	v_pk_mul_f32 v[94:95], s[14:15], v[94:95] op_sel_hi:[0,1]
	v_pk_mul_f32 v[96:97], s[14:15], v[96:97] op_sel_hi:[0,1]
	v_pk_mul_f32 v[90:91], s[14:15], v[90:91] op_sel_hi:[0,1]
	v_pk_mul_f32 v[92:93], s[14:15], v[92:93] op_sel_hi:[0,1]
	v_pk_mul_f32 v[86:87], s[14:15], v[86:87] op_sel_hi:[0,1]
	v_pk_mul_f32 v[88:89], s[14:15], v[88:89] op_sel_hi:[0,1]
	v_pk_mul_f32 v[82:83], s[14:15], v[82:83] op_sel_hi:[0,1]
	v_pk_mul_f32 v[84:85], s[14:15], v[84:85] op_sel_hi:[0,1]
	v_cvt_pk_bf16_f32 v94, v94, v95
	v_cvt_pk_bf16_f32 v95, v96, v97
	v_cvt_pk_bf16_f32 v96, v90, v91
	v_cvt_pk_bf16_f32 v97, v92, v93
	global_store_dwordx4 v22, v[94:97], s[12:13]
	v_cvt_pk_bf16_f32 v86, v86, v87
	v_cvt_pk_bf16_f32 v87, v88, v89
	v_cvt_pk_bf16_f32 v88, v82, v83
	v_cvt_pk_bf16_f32 v89, v84, v85
	global_store_dwordx4 v22, v[86:89], s[12:13] offset:64
	s_add_u32 s12, s12, s20
	s_addc_u32 s13, s13, 0
	v_pk_mul_f32 v[78:79], s[14:15], v[78:79] op_sel_hi:[0,1]
	v_pk_mul_f32 v[80:81], s[14:15], v[80:81] op_sel_hi:[0,1]
	v_pk_mul_f32 v[74:75], s[14:15], v[74:75] op_sel_hi:[0,1]
	v_pk_mul_f32 v[76:77], s[14:15], v[76:77] op_sel_hi:[0,1]
	v_pk_mul_f32 v[70:71], s[14:15], v[70:71] op_sel_hi:[0,1]
	v_pk_mul_f32 v[72:73], s[14:15], v[72:73] op_sel_hi:[0,1]
	v_pk_mul_f32 v[66:67], s[14:15], v[66:67] op_sel_hi:[0,1]
	v_pk_mul_f32 v[68:69], s[14:15], v[68:69] op_sel_hi:[0,1]
	v_cvt_pk_bf16_f32 v78, v78, v79
	v_cvt_pk_bf16_f32 v79, v80, v81
	v_cvt_pk_bf16_f32 v80, v74, v75
	v_cvt_pk_bf16_f32 v81, v76, v77
	global_store_dwordx4 v22, v[78:81], s[12:13]
	v_cvt_pk_bf16_f32 v70, v70, v71
	v_cvt_pk_bf16_f32 v71, v72, v73
	v_cvt_pk_bf16_f32 v72, v66, v67
	v_cvt_pk_bf16_f32 v73, v68, v69
	global_store_dwordx4 v22, v[70:73], s[12:13] offset:64
.Lqkv_done:
	s_mov_b64 s[10:11], 0
.LBB0_253:
	s_and_b64 vcc, exec, s[10:11]
	v_readlane_b32 s22, v255, 18
	v_readlane_b32 s23, v255, 19
	s_mov_b64 s[24:25], s[74:75]
	s_mov_b64 s[74:75], s[50:51]
	s_mov_b64 s[50:51], s[46:47]
	s_mov_b64 s[46:47], s[16:17]
	s_mov_b64 s[16:17], s[48:49]
	s_mov_b64 s[48:49], s[68:69]
	s_mov_b64 s[68:69], s[38:39]
	s_mov_b32 s39, s77
	s_cbranch_vccz .LBB0_257
	v_cmp_eq_u32_e32 vcc, 0, v244
	s_and_saveexec_b64 s[6:7], vcc
	s_cbranch_execz .LBB0_256
	v_readlane_b32 s10, v255, 45
	v_readlane_b32 s76, v255, 49
	v_readlane_b32 s11, v255, 46
	v_readlane_b32 s77, v255, 50
	s_add_u32 s10, s76, s10
	s_addc_u32 s11, s77, s11
	v_and_b32_e32 v2, 0xff, v19
	s_add_i32 s12, 0, 0x20100
	global_load_dword v8, v1, s[10:11]
	global_load_dword v9, v1, s[10:11] offset:4
	global_load_dword v10, v1, s[10:11] offset:8
	global_load_dword v11, v1, s[10:11] offset:12
	global_load_dword v12, v1, s[10:11] offset:16
	global_load_dword v13, v1, s[10:11] offset:20
	v_lshl_add_u32 v2, v2, 2, s12
	ds_read_b32 v4, v2
	s_mov_b32 s14, 0xbfb8aa3b
	v_ashrrev_i32_e32 v19, 31, v18
	v_readlane_b32 s20, v255, 37
	v_lshlrev_b64 v[2:3], 5, v[18:19]
	v_readlane_b32 s21, v255, 38
	v_readlane_b32 s78, v255, 51
	v_readlane_b32 s79, v255, 52
	v_lshl_add_u64 v[2:3], s[20:21], 0, v[2:3]
	s_waitcnt vmcnt(0) lgkmcnt(0)
	v_mov_b32_e32 v5, v8
	v_fmac_f32_e32 v5, v190, v4
	v_min_f32_e32 v6, 0, v5
	v_mul_f32_e64 v5, |v5|, s14
	v_exp_f32_e32 v5, v5
	s_nop 0
	v_add_f32_e32 v5, 1.0, v5
	v_log_f32_e32 v5, v5
	s_nop 0
	v_fmac_f32_e32 v6, 0xbf317218, v5
	global_store_dword v[2:3], v6, off
	v_mov_b32_e32 v5, v9
	v_fmac_f32_e32 v5, v191, v4
	v_min_f32_e32 v6, 0, v5
	v_mul_f32_e64 v5, |v5|, s14
	v_exp_f32_e32 v5, v5
	s_nop 0
	v_add_f32_e32 v5, 1.0, v5
	v_log_f32_e32 v5, v5
	s_nop 0
	v_fmac_f32_e32 v6, 0xbf317218, v5
	global_store_dword v[2:3], v6, off offset:4
	v_mov_b32_e32 v5, v10
	v_fmac_f32_e32 v5, v192, v4
	v_min_f32_e32 v6, 0, v5
	v_mul_f32_e64 v5, |v5|, s14
	v_exp_f32_e32 v5, v5
	s_nop 0
	v_add_f32_e32 v5, 1.0, v5
	v_log_f32_e32 v5, v5
	s_nop 0
	v_fmac_f32_e32 v6, 0xbf317218, v5
	global_store_dword v[2:3], v6, off offset:8
	v_mov_b32_e32 v5, v11
	v_fmac_f32_e32 v5, v193, v4
	v_min_f32_e32 v6, 0, v5
	v_mul_f32_e64 v5, |v5|, s14
	v_exp_f32_e32 v5, v5
	s_nop 0
	v_add_f32_e32 v5, 1.0, v5
	v_log_f32_e32 v5, v5
	s_nop 0
	v_fmac_f32_e32 v6, 0xbf317218, v5
	global_store_dword v[2:3], v6, off offset:12
	v_mov_b32_e32 v5, v12
	v_fmac_f32_e32 v5, v186, v4
	v_min_f32_e32 v6, 0, v5
	v_mul_f32_e64 v5, |v5|, s14
	v_exp_f32_e32 v5, v5
	s_nop 0
	v_add_f32_e32 v5, 1.0, v5
	v_log_f32_e32 v5, v5
	s_nop 0
	v_fmac_f32_e32 v6, 0xbf317218, v5
	global_store_dword v[2:3], v6, off offset:16
	v_mov_b32_e32 v5, v13
	v_fmac_f32_e32 v5, v187, v4
	v_min_f32_e32 v4, 0, v5
	v_mul_f32_e64 v5, |v5|, s14
	v_exp_f32_e32 v5, v5
	s_nop 0
	v_add_f32_e32 v5, 1.0, v5
	v_log_f32_e32 v5, v5
	s_nop 0
	v_fmac_f32_e32 v4, 0xbf317218, v5
	global_store_dword v[2:3], v4, off offset:20
	v_mov_b32_e32 v5, v8
	v_add_u32_e32 v2, 16, v18
	v_and_b32_e32 v3, 0xff, v2
	v_lshl_add_u32 v3, v3, 2, s12
	ds_read_b32 v4, v3
	v_ashrrev_i32_e32 v3, 31, v2
	v_lshlrev_b64 v[2:3], 5, v[2:3]
	v_lshl_add_u64 v[2:3], s[20:21], 0, v[2:3]
	s_waitcnt lgkmcnt(0)
; __device__ __forceinline__ float fexp2(float x) { return __builtin_amdgcn_exp2f(x); }
; __device__ __forceinline__ float flog2(float x) { return __builtin_amdgcn_logf(x); }
;     __device__ __forceinline__ void operator()(AccRef acc, const pg8::Unit& u, int wr, int wc, int fr, int fq) const {
;     ...
;         if (G == 78) {
;             if (fq == 0) {
; #pragma unroll
;                 for (int ai = 0; ai < 2; ++ai)
; #pragma unroll
;                     for (int m = 0; m < 4; ++m) {
;                         const int row = row0 + ai * 128 + m * 16;
;                         const float rsr = rst[row & 255];
; #pragma unroll
;                         for (int e = 0; e < 6; ++e) {
;                             const float x = acc[ai][0][m][e >> 2][e & 3] * rsr + fb[e];
;                             const float ls = fminf(x, 0.f) - LN2 * flog2(1.0f + fexp2(-fabsf(x) * LOG2E));
;                             logf[(size_t)row * 8 + e] = ls;
;                         }
;                     }
;             }
	v_fmac_f32_e32 v5, v174, v4
	v_min_f32_e32 v6, 0, v5
	v_mul_f32_e64 v5, |v5|, s14
	v_exp_f32_e32 v5, v5
	s_nop 0
	v_add_f32_e32 v5, 1.0, v5
	v_log_f32_e32 v5, v5
	s_nop 0
	v_fmac_f32_e32 v6, 0xbf317218, v5
	global_store_dword v[2:3], v6, off
	v_mov_b32_e32 v5, v9
	v_fmac_f32_e32 v5, v175, v4
	v_min_f32_e32 v6, 0, v5
	v_mul_f32_e64 v5, |v5|, s14
	v_exp_f32_e32 v5, v5
	s_nop 0
	v_add_f32_e32 v5, 1.0, v5
	v_log_f32_e32 v5, v5
	s_nop 0
	v_fmac_f32_e32 v6, 0xbf317218, v5
	global_store_dword v[2:3], v6, off offset:4
	v_mov_b32_e32 v5, v10
	v_fmac_f32_e32 v5, v176, v4
	v_min_f32_e32 v6, 0, v5
	v_mul_f32_e64 v5, |v5|, s14
	v_exp_f32_e32 v5, v5
	s_nop 0
	v_add_f32_e32 v5, 1.0, v5
	v_log_f32_e32 v5, v5
	s_nop 0
	v_fmac_f32_e32 v6, 0xbf317218, v5
	global_store_dword v[2:3], v6, off offset:8
	v_mov_b32_e32 v5, v11
	v_fmac_f32_e32 v5, v177, v4
	v_min_f32_e32 v6, 0, v5
	v_mul_f32_e64 v5, |v5|, s14
	v_exp_f32_e32 v5, v5
	s_nop 0
	v_add_f32_e32 v5, 1.0, v5
	v_log_f32_e32 v5, v5
	s_nop 0
	v_fmac_f32_e32 v6, 0xbf317218, v5
	global_store_dword v[2:3], v6, off offset:12
	v_mov_b32_e32 v5, v12
	v_fmac_f32_e32 v5, v170, v4
	v_min_f32_e32 v6, 0, v5
	v_mul_f32_e64 v5, |v5|, s14
	v_exp_f32_e32 v5, v5
	s_nop 0
	v_add_f32_e32 v5, 1.0, v5
	v_log_f32_e32 v5, v5
	s_nop 0
	v_fmac_f32_e32 v6, 0xbf317218, v5
	global_store_dword v[2:3], v6, off offset:16
	v_mov_b32_e32 v5, v13
	v_fmac_f32_e32 v5, v171, v4
	v_min_f32_e32 v4, 0, v5
	v_mul_f32_e64 v5, |v5|, s14
	v_exp_f32_e32 v5, v5
	s_nop 0
	v_add_f32_e32 v5, 1.0, v5
	v_log_f32_e32 v5, v5
	s_nop 0
	v_fmac_f32_e32 v4, 0xbf317218, v5
	global_store_dword v[2:3], v4, off offset:20
	v_mov_b32_e32 v5, v8
	v_add_u32_e32 v2, 32, v18
	v_and_b32_e32 v3, 0xff, v2
	v_lshl_add_u32 v3, v3, 2, s12
	ds_read_b32 v4, v3
	v_ashrrev_i32_e32 v3, 31, v2
	v_lshlrev_b64 v[2:3], 5, v[2:3]
	v_lshl_add_u64 v[2:3], s[20:21], 0, v[2:3]
	s_waitcnt lgkmcnt(0)
	v_fmac_f32_e32 v5, v158, v4
	v_min_f32_e32 v6, 0, v5
	v_mul_f32_e64 v5, |v5|, s14
	v_exp_f32_e32 v5, v5
	s_nop 0
	v_add_f32_e32 v5, 1.0, v5
	v_log_f32_e32 v5, v5
	s_nop 0
	v_fmac_f32_e32 v6, 0xbf317218, v5
	global_store_dword v[2:3], v6, off
	v_mov_b32_e32 v5, v9
	v_fmac_f32_e32 v5, v159, v4
	v_min_f32_e32 v6, 0, v5
	v_mul_f32_e64 v5, |v5|, s14
	v_exp_f32_e32 v5, v5
	s_nop 0
	v_add_f32_e32 v5, 1.0, v5
	v_log_f32_e32 v5, v5
	s_nop 0
	v_fmac_f32_e32 v6, 0xbf317218, v5
	global_store_dword v[2:3], v6, off offset:4
	v_mov_b32_e32 v5, v10
	v_fmac_f32_e32 v5, v160, v4
	v_min_f32_e32 v6, 0, v5
	v_mul_f32_e64 v5, |v5|, s14
	v_exp_f32_e32 v5, v5
	s_nop 0
	v_add_f32_e32 v5, 1.0, v5
	v_log_f32_e32 v5, v5
	s_nop 0
	v_fmac_f32_e32 v6, 0xbf317218, v5
	global_store_dword v[2:3], v6, off offset:8
	v_mov_b32_e32 v5, v11
	v_fmac_f32_e32 v5, v161, v4
	v_min_f32_e32 v6, 0, v5
	v_mul_f32_e64 v5, |v5|, s14
	v_exp_f32_e32 v5, v5
	s_nop 0
	v_add_f32_e32 v5, 1.0, v5
	v_log_f32_e32 v5, v5
	s_nop 0
	v_fmac_f32_e32 v6, 0xbf317218, v5
	global_store_dword v[2:3], v6, off offset:12
	v_mov_b32_e32 v5, v12
	v_fmac_f32_e32 v5, v154, v4
	v_min_f32_e32 v6, 0, v5
	v_mul_f32_e64 v5, |v5|, s14
	v_exp_f32_e32 v5, v5
	s_nop 0
	v_add_f32_e32 v5, 1.0, v5
	v_log_f32_e32 v5, v5
	s_nop 0
	v_fmac_f32_e32 v6, 0xbf317218, v5
	global_store_dword v[2:3], v6, off offset:16
	v_mov_b32_e32 v5, v13
	v_fmac_f32_e32 v5, v155, v4
	v_min_f32_e32 v4, 0, v5
	v_mul_f32_e64 v5, |v5|, s14
	v_exp_f32_e32 v5, v5
	s_nop 0
	v_add_f32_e32 v5, 1.0, v5
	v_log_f32_e32 v5, v5
	s_nop 0
	v_fmac_f32_e32 v4, 0xbf317218, v5
	global_store_dword v[2:3], v4, off offset:20
	v_mov_b32_e32 v5, v8
	v_add_u32_e32 v2, 48, v18
	v_and_b32_e32 v3, 0xff, v2
	v_lshl_add_u32 v3, v3, 2, s12
	ds_read_b32 v4, v3
	v_ashrrev_i32_e32 v3, 31, v2
	v_lshlrev_b64 v[2:3], 5, v[2:3]
	v_lshl_add_u64 v[2:3], s[20:21], 0, v[2:3]
	s_waitcnt lgkmcnt(0)
	v_fmac_f32_e32 v5, v142, v4
	v_min_f32_e32 v6, 0, v5
	v_mul_f32_e64 v5, |v5|, s14
	v_exp_f32_e32 v5, v5
	s_nop 0
	v_add_f32_e32 v5, 1.0, v5
	v_log_f32_e32 v5, v5
	s_nop 0
	v_fmac_f32_e32 v6, 0xbf317218, v5
	global_store_dword v[2:3], v6, off
	v_mov_b32_e32 v5, v9
	v_fmac_f32_e32 v5, v143, v4
	v_min_f32_e32 v6, 0, v5
	v_mul_f32_e64 v5, |v5|, s14
	v_exp_f32_e32 v5, v5
	s_nop 0
	v_add_f32_e32 v5, 1.0, v5
	v_log_f32_e32 v5, v5
	s_nop 0
	v_fmac_f32_e32 v6, 0xbf317218, v5
	global_store_dword v[2:3], v6, off offset:4
	v_mov_b32_e32 v5, v10
	v_fmac_f32_e32 v5, v144, v4
	v_min_f32_e32 v6, 0, v5
	v_mul_f32_e64 v5, |v5|, s14
	v_exp_f32_e32 v5, v5
	s_nop 0
	v_add_f32_e32 v5, 1.0, v5
	v_log_f32_e32 v5, v5
	s_nop 0
	v_fmac_f32_e32 v6, 0xbf317218, v5
	global_store_dword v[2:3], v6, off offset:8
	v_mov_b32_e32 v5, v11
	v_fmac_f32_e32 v5, v145, v4
	v_min_f32_e32 v6, 0, v5
	v_mul_f32_e64 v5, |v5|, s14
	v_exp_f32_e32 v5, v5
	s_nop 0
	v_add_f32_e32 v5, 1.0, v5
	v_log_f32_e32 v5, v5
	s_nop 0
	v_fmac_f32_e32 v6, 0xbf317218, v5
	global_store_dword v[2:3], v6, off offset:12
	v_mov_b32_e32 v5, v12
	v_fmac_f32_e32 v5, v138, v4
	v_min_f32_e32 v6, 0, v5
	v_mul_f32_e64 v5, |v5|, s14
	v_exp_f32_e32 v5, v5
	s_nop 0
	v_add_f32_e32 v5, 1.0, v5
	v_log_f32_e32 v5, v5
	s_nop 0
	v_fmac_f32_e32 v6, 0xbf317218, v5
	global_store_dword v[2:3], v6, off offset:16
	v_mov_b32_e32 v5, v13
	v_fmac_f32_e32 v5, v139, v4
	v_min_f32_e32 v4, 0, v5
	v_mul_f32_e64 v5, |v5|, s14
	v_exp_f32_e32 v5, v5
	s_nop 0
	v_add_f32_e32 v5, 1.0, v5
	v_log_f32_e32 v5, v5
	s_nop 0
	v_fmac_f32_e32 v4, 0xbf317218, v5
	global_store_dword v[2:3], v4, off offset:20
	v_mov_b32_e32 v5, v8
	v_add_u32_e32 v2, 0x80, v18
	v_and_b32_e32 v3, 0xff, v2
	v_lshl_add_u32 v3, v3, 2, s12
	ds_read_b32 v4, v3
	v_ashrrev_i32_e32 v3, 31, v2
	v_lshlrev_b64 v[2:3], 5, v[2:3]
	v_lshl_add_u64 v[2:3], s[20:21], 0, v[2:3]
	s_waitcnt lgkmcnt(0)
; __device__ __forceinline__ float fexp2(float x) { return __builtin_amdgcn_exp2f(x); }
; __device__ __forceinline__ float flog2(float x) { return __builtin_amdgcn_logf(x); }
;     __device__ __forceinline__ void operator()(AccRef acc, const pg8::Unit& u, int wr, int wc, int fr, int fq) const {
;     ...
;         if (G == 78) {
;             if (fq == 0) {
; #pragma unroll
;                 for (int ai = 0; ai < 2; ++ai)
; #pragma unroll
;                     for (int m = 0; m < 4; ++m) {
;                         const int row = row0 + ai * 128 + m * 16;
;                         const float rsr = rst[row & 255];
; #pragma unroll
;                         for (int e = 0; e < 6; ++e) {
;                             const float x = acc[ai][0][m][e >> 2][e & 3] * rsr + fb[e];
;                             const float ls = fminf(x, 0.f) - LN2 * flog2(1.0f + fexp2(-fabsf(x) * LOG2E));
;                             logf[(size_t)row * 8 + e] = ls;
;                         }
;                     }
;             }
	v_fmac_f32_e32 v5, v126, v4
	v_min_f32_e32 v6, 0, v5
	v_mul_f32_e64 v5, |v5|, s14
	v_exp_f32_e32 v5, v5
	s_nop 0
	v_add_f32_e32 v5, 1.0, v5
	v_log_f32_e32 v5, v5
	s_nop 0
	v_fmac_f32_e32 v6, 0xbf317218, v5
	global_store_dword v[2:3], v6, off
	v_mov_b32_e32 v5, v9
	v_fmac_f32_e32 v5, v127, v4
	v_min_f32_e32 v6, 0, v5
	v_mul_f32_e64 v5, |v5|, s14
	v_exp_f32_e32 v5, v5
	s_nop 0
	v_add_f32_e32 v5, 1.0, v5
	v_log_f32_e32 v5, v5
	s_nop 0
	v_fmac_f32_e32 v6, 0xbf317218, v5
	global_store_dword v[2:3], v6, off offset:4
	v_mov_b32_e32 v5, v10
	v_fmac_f32_e32 v5, v128, v4
	v_min_f32_e32 v6, 0, v5
	v_mul_f32_e64 v5, |v5|, s14
	v_exp_f32_e32 v5, v5
	s_nop 0
	v_add_f32_e32 v5, 1.0, v5
	v_log_f32_e32 v5, v5
	s_nop 0
	v_fmac_f32_e32 v6, 0xbf317218, v5
	global_store_dword v[2:3], v6, off offset:8
	v_mov_b32_e32 v5, v11
	v_fmac_f32_e32 v5, v129, v4
	v_min_f32_e32 v6, 0, v5
	v_mul_f32_e64 v5, |v5|, s14
	v_exp_f32_e32 v5, v5
	s_nop 0
	v_add_f32_e32 v5, 1.0, v5
	v_log_f32_e32 v5, v5
	s_nop 0
	v_fmac_f32_e32 v6, 0xbf317218, v5
	global_store_dword v[2:3], v6, off offset:12
	v_mov_b32_e32 v5, v12
	v_fmac_f32_e32 v5, v122, v4
	v_min_f32_e32 v6, 0, v5
	v_mul_f32_e64 v5, |v5|, s14
	v_exp_f32_e32 v5, v5
	s_nop 0
	v_add_f32_e32 v5, 1.0, v5
	v_log_f32_e32 v5, v5
	s_nop 0
	v_fmac_f32_e32 v6, 0xbf317218, v5
	global_store_dword v[2:3], v6, off offset:16
	v_mov_b32_e32 v5, v13
	v_fmac_f32_e32 v5, v123, v4
	v_min_f32_e32 v4, 0, v5
	v_mul_f32_e64 v5, |v5|, s14
	v_exp_f32_e32 v5, v5
	s_nop 0
	v_add_f32_e32 v5, 1.0, v5
	v_log_f32_e32 v5, v5
	s_nop 0
	v_fmac_f32_e32 v4, 0xbf317218, v5
	global_store_dword v[2:3], v4, off offset:20
	v_mov_b32_e32 v5, v8
	v_add_u32_e32 v2, 0x90, v18
	v_and_b32_e32 v3, 0xff, v2
	v_lshl_add_u32 v3, v3, 2, s12
	ds_read_b32 v4, v3
	v_ashrrev_i32_e32 v3, 31, v2
	v_lshlrev_b64 v[2:3], 5, v[2:3]
	v_lshl_add_u64 v[2:3], s[20:21], 0, v[2:3]
	s_waitcnt lgkmcnt(0)
	v_fmac_f32_e32 v5, v110, v4
	v_min_f32_e32 v6, 0, v5
	v_mul_f32_e64 v5, |v5|, s14
	v_exp_f32_e32 v5, v5
	s_nop 0
	v_add_f32_e32 v5, 1.0, v5
	v_log_f32_e32 v5, v5
	s_nop 0
	v_fmac_f32_e32 v6, 0xbf317218, v5
	global_store_dword v[2:3], v6, off
	v_mov_b32_e32 v5, v9
	v_fmac_f32_e32 v5, v111, v4
	v_min_f32_e32 v6, 0, v5
	v_mul_f32_e64 v5, |v5|, s14
	v_exp_f32_e32 v5, v5
	s_nop 0
	v_add_f32_e32 v5, 1.0, v5
	v_log_f32_e32 v5, v5
	s_nop 0
	v_fmac_f32_e32 v6, 0xbf317218, v5
	global_store_dword v[2:3], v6, off offset:4
	v_mov_b32_e32 v5, v10
	v_fmac_f32_e32 v5, v112, v4
	v_min_f32_e32 v6, 0, v5
	v_mul_f32_e64 v5, |v5|, s14
	v_exp_f32_e32 v5, v5
	s_nop 0
	v_add_f32_e32 v5, 1.0, v5
	v_log_f32_e32 v5, v5
	s_nop 0
	v_fmac_f32_e32 v6, 0xbf317218, v5
	global_store_dword v[2:3], v6, off offset:8
	v_mov_b32_e32 v5, v11
	v_fmac_f32_e32 v5, v113, v4
	v_min_f32_e32 v6, 0, v5
	v_mul_f32_e64 v5, |v5|, s14
	v_exp_f32_e32 v5, v5
	s_nop 0
	v_add_f32_e32 v5, 1.0, v5
	v_log_f32_e32 v5, v5
	s_nop 0
	v_fmac_f32_e32 v6, 0xbf317218, v5
	global_store_dword v[2:3], v6, off offset:12
	v_mov_b32_e32 v5, v12
	v_fmac_f32_e32 v5, v106, v4
	v_min_f32_e32 v6, 0, v5
	v_mul_f32_e64 v5, |v5|, s14
	v_exp_f32_e32 v5, v5
	s_nop 0
	v_add_f32_e32 v5, 1.0, v5
	v_log_f32_e32 v5, v5
	s_nop 0
	v_fmac_f32_e32 v6, 0xbf317218, v5
	global_store_dword v[2:3], v6, off offset:16
	v_mov_b32_e32 v5, v13
	v_fmac_f32_e32 v5, v107, v4
	v_min_f32_e32 v4, 0, v5
	v_mul_f32_e64 v5, |v5|, s14
	v_exp_f32_e32 v5, v5
	s_nop 0
	v_add_f32_e32 v5, 1.0, v5
	v_log_f32_e32 v5, v5
	s_nop 0
	v_fmac_f32_e32 v4, 0xbf317218, v5
	global_store_dword v[2:3], v4, off offset:20
	v_mov_b32_e32 v5, v8
	v_add_u32_e32 v2, 0xa0, v18
	v_and_b32_e32 v3, 0xff, v2
	v_lshl_add_u32 v3, v3, 2, s12
	ds_read_b32 v4, v3
	v_ashrrev_i32_e32 v3, 31, v2
	v_lshlrev_b64 v[2:3], 5, v[2:3]
	v_lshl_add_u64 v[2:3], s[20:21], 0, v[2:3]
	s_waitcnt lgkmcnt(0)
; __device__ __forceinline__ float fexp2(float x) { return __builtin_amdgcn_exp2f(x); }
; __device__ __forceinline__ float flog2(float x) { return __builtin_amdgcn_logf(x); }
;     __device__ __forceinline__ void operator()(AccRef acc, const pg8::Unit& u, int wr, int wc, int fr, int fq) const {
;     ...
;         if (G == 78) {
;             if (fq == 0) {
; #pragma unroll
;                 for (int ai = 0; ai < 2; ++ai)
; #pragma unroll
;                     for (int m = 0; m < 4; ++m) {
;                         const int row = row0 + ai * 128 + m * 16;
;                         const float rsr = rst[row & 255];
; #pragma unroll
;                         for (int e = 0; e < 6; ++e) {
;                             const float x = acc[ai][0][m][e >> 2][e & 3] * rsr + fb[e];
;                             const float ls = fminf(x, 0.f) - LN2 * flog2(1.0f + fexp2(-fabsf(x) * LOG2E));
;                             logf[(size_t)row * 8 + e] = ls;
;                         }
;                     }
;             }
	v_fmac_f32_e32 v5, v94, v4
	v_min_f32_e32 v6, 0, v5
	v_mul_f32_e64 v5, |v5|, s14
	v_exp_f32_e32 v5, v5
	s_nop 0
	v_add_f32_e32 v5, 1.0, v5
	v_log_f32_e32 v5, v5
	s_nop 0
	v_fmac_f32_e32 v6, 0xbf317218, v5
	global_store_dword v[2:3], v6, off
	v_mov_b32_e32 v5, v9
	v_fmac_f32_e32 v5, v95, v4
	v_min_f32_e32 v6, 0, v5
	v_mul_f32_e64 v5, |v5|, s14
	v_exp_f32_e32 v5, v5
	s_nop 0
	v_add_f32_e32 v5, 1.0, v5
	v_log_f32_e32 v5, v5
	s_nop 0
	v_fmac_f32_e32 v6, 0xbf317218, v5
	global_store_dword v[2:3], v6, off offset:4
	v_mov_b32_e32 v5, v10
	v_fmac_f32_e32 v5, v96, v4
	v_min_f32_e32 v6, 0, v5
	v_mul_f32_e64 v5, |v5|, s14
	v_exp_f32_e32 v5, v5
	s_nop 0
	v_add_f32_e32 v5, 1.0, v5
	v_log_f32_e32 v5, v5
	s_nop 0
	v_fmac_f32_e32 v6, 0xbf317218, v5
	global_store_dword v[2:3], v6, off offset:8
	v_mov_b32_e32 v5, v11
	v_fmac_f32_e32 v5, v97, v4
	v_min_f32_e32 v6, 0, v5
	v_mul_f32_e64 v5, |v5|, s14
	v_exp_f32_e32 v5, v5
	s_nop 0
	v_add_f32_e32 v5, 1.0, v5
	v_log_f32_e32 v5, v5
	s_nop 0
	v_fmac_f32_e32 v6, 0xbf317218, v5
	global_store_dword v[2:3], v6, off offset:12
	v_mov_b32_e32 v5, v12
	v_fmac_f32_e32 v5, v90, v4
	v_min_f32_e32 v6, 0, v5
	v_mul_f32_e64 v5, |v5|, s14
	v_exp_f32_e32 v5, v5
	s_nop 0
	v_add_f32_e32 v5, 1.0, v5
	v_log_f32_e32 v5, v5
	s_nop 0
	v_fmac_f32_e32 v6, 0xbf317218, v5
	global_store_dword v[2:3], v6, off offset:16
	v_mov_b32_e32 v5, v13
	v_fmac_f32_e32 v5, v91, v4
	v_min_f32_e32 v4, 0, v5
	v_mul_f32_e64 v5, |v5|, s14
	v_exp_f32_e32 v5, v5
	s_nop 0
	v_add_f32_e32 v5, 1.0, v5
	v_log_f32_e32 v5, v5
	s_nop 0
	v_fmac_f32_e32 v4, 0xbf317218, v5
	global_store_dword v[2:3], v4, off offset:20
	v_mov_b32_e32 v5, v8
	v_add_u32_e32 v2, 0xb0, v18
	v_and_b32_e32 v3, 0xff, v2
	v_lshl_add_u32 v3, v3, 2, s12
	ds_read_b32 v4, v3
	v_ashrrev_i32_e32 v3, 31, v2
	v_lshlrev_b64 v[2:3], 5, v[2:3]
	v_lshl_add_u64 v[2:3], s[20:21], 0, v[2:3]
	s_waitcnt lgkmcnt(0)
	v_fmac_f32_e32 v5, v78, v4
	v_min_f32_e32 v6, 0, v5
	v_mul_f32_e64 v5, |v5|, s14
	v_exp_f32_e32 v5, v5
	s_nop 0
	v_add_f32_e32 v5, 1.0, v5
	v_log_f32_e32 v5, v5
	s_nop 0
	v_fmac_f32_e32 v6, 0xbf317218, v5
	global_store_dword v[2:3], v6, off
	v_mov_b32_e32 v5, v9
	v_fmac_f32_e32 v5, v79, v4
	v_min_f32_e32 v6, 0, v5
	v_mul_f32_e64 v5, |v5|, s14
	v_exp_f32_e32 v5, v5
	s_nop 0
	v_add_f32_e32 v5, 1.0, v5
	v_log_f32_e32 v5, v5
	s_nop 0
	v_fmac_f32_e32 v6, 0xbf317218, v5
	global_store_dword v[2:3], v6, off offset:4
	v_mov_b32_e32 v5, v10
	v_fmac_f32_e32 v5, v80, v4
	v_min_f32_e32 v6, 0, v5
	v_mul_f32_e64 v5, |v5|, s14
	v_exp_f32_e32 v5, v5
	s_nop 0
	v_add_f32_e32 v5, 1.0, v5
	v_log_f32_e32 v5, v5
	s_nop 0
	v_fmac_f32_e32 v6, 0xbf317218, v5
	global_store_dword v[2:3], v6, off offset:8
	v_mov_b32_e32 v5, v11
	v_fmac_f32_e32 v5, v81, v4
	v_min_f32_e32 v6, 0, v5
	v_mul_f32_e64 v5, |v5|, s14
	v_exp_f32_e32 v5, v5
	s_nop 0
	v_add_f32_e32 v5, 1.0, v5
	v_log_f32_e32 v5, v5
	s_nop 0
	v_fmac_f32_e32 v6, 0xbf317218, v5
	global_store_dword v[2:3], v6, off offset:12
	v_mov_b32_e32 v5, v12
	v_fmac_f32_e32 v5, v74, v4
	v_min_f32_e32 v6, 0, v5
	v_mul_f32_e64 v5, |v5|, s14
	v_exp_f32_e32 v5, v5
	s_nop 0
	v_add_f32_e32 v5, 1.0, v5
	v_log_f32_e32 v5, v5
	s_nop 0
	v_fmac_f32_e32 v6, 0xbf317218, v5
	global_store_dword v[2:3], v6, off offset:16
	v_mov_b32_e32 v5, v13
	v_fmac_f32_e32 v5, v75, v4
	v_min_f32_e32 v4, 0, v5
	v_mul_f32_e64 v5, |v5|, s14
	v_exp_f32_e32 v5, v5
	s_nop 0
	v_add_f32_e32 v5, 1.0, v5
	v_log_f32_e32 v5, v5
	s_nop 0
	v_fmac_f32_e32 v4, 0xbf317218, v5
	global_store_dword v[2:3], v4, off offset:20
